# V^T tile epilogue of the K|V up-projection: transposed through LDS and stored as 16-byte row pieces instead of 2-byte scattered stores
# speedup vs baseline: 1.0051x; 1.0051x over previous
; DI unsigned short f2bf(float f) { return (unsigned short)(cvtpk(f, 0.f) & 0xffffu); }
;     __device__ __forceinline__ static u32x4 pack8(const f32x4& a, const f32x4& b) { u32x4 w; w.x = cvtpk(a[0], a[1]); w.y = cvtpk(a[2], a[3]); w.z = cvtpk(b[0], b[1]); w.w = cvtpk(b[2], b[3]); return w; }
;     __device__ __forceinline__ float rstd_row(const sq_t* sq, int row, float invn) const { return rs_on ? rs_lds[row - rs_base] : rstd_of(sq, row, invn); }
;     __device__ __forceinline__ void operator()(const f32x4 (&acc)[2][2][4][2], const Unit& u, int wr, int wc, int fr, int fq) const {
;     ...
;         } else if (mode == EM_K || mode == EM_V) {
;             bf16_t* kbase = (bf16_t*)(ws + WS_K); bf16_t* vbase = (bf16_t*)(ws + WS_VT);
; #pragma unroll
;             for (int ai = 0; ai < 2; ++ai)
; #pragma unroll
;                 for (int m = 0; m < 4; ++m) { const int row = row0 + ai * HALF + m * 16, pos = row & (S - 1), seq = row >> sshift; const float r = rstd_row(SQKV, row, 1.f / 256.f);
; #pragma unroll
;                     for (int bj = 0; bj < 2; ++bj) { const int C0 = (pn & 1) * 256 + bj * HALF + cw, head = C0 >> 6, w = C0 & 63;
;                         const f32x4 v0 = acc[ai][bj][m][0] * r, v1 = acc[ai][bj][m][1] * r;
;                         if (pn < 2) *(u32x4*)(kbase + (size_t)row * 768 + head * 96 + w) = pack8(v0, v1);
;                         else { bf16_t* vp = vbase + ((size_t)((seq * 8 + head) * 64 + w)) * S + pos;
;                             vp[0] = f2bf(v0[0]); vp[(size_t)S] = f2bf(v0[1]); vp[(size_t)2 * S] = f2bf(v0[2]); vp[(size_t)3 * S] = f2bf(v0[3]);
;                             vp[(size_t)4 * S] = f2bf(v1[0]); vp[(size_t)5 * S] = f2bf(v1[1]); vp[(size_t)6 * S] = f2bf(v1[2]); vp[(size_t)7 * S] = f2bf(v1[3]); } } }
.LBB0_821:
	s_cmp_lt_i32 s2, 2
	s_cbranch_scc1 .Lkv_orig
	s_and_b64 vcc, exec, s[16:17]
	s_cbranch_vccz .Lkv_orig
	s_and_b64 vcc, exec, s[6:7]
	s_cbranch_vccz .Lkv_orig
	v_mbcnt_lo_u32_b32 v168, -1, 0
	v_mbcnt_hi_u32_b32 v168, -1, v168
	v_readlane_b32 s84, v254, 7
	s_lshr_b32 s10, s84, 2
	s_and_b32 s11, s84, 3
	v_and_b32_e32 v169, 15, v168
	v_lshrrev_b32_e32 v172, 4, v168
	s_mul_i32 s12, s11, 0x4200
	s_lshl_b32 s13, s10, 7
	s_add_i32 s12, s12, s13
	v_mul_u32_u24_e32 v173, 0x1080, v172
	v_lshl_add_u32 v173, v169, 1, v173
	v_add_u32_e32 v173, s12, v173
	s_mul_i32 s12, s84, 0x2100
	v_lshrrev_b32_e32 v184, 5, v168
	v_mul_u32_u24_e32 v176, 0x210, v184
	v_and_b32_e32 v204, 31, v168
	v_lshl_add_u32 v176, v204, 4, v176
	v_add_u32_e32 v176, s12, v176
	s_lshl_b32 s12, s3, 8
	s_lshl_b32 s13, s10, 6
	s_add_i32 s13, s12, s13
	s_sub_i32 s13, s13, s59
	s_lshl_b32 s13, s13, 2
	s_add_i32 s13, s13, 0x20040
	v_lshl_add_u32 v180, v169, 2, s13
	s_lshr_b32 s4, s12, s33
	s_and_b32 s5, s12, s74
	s_lshl_b32 s4, s4, 9
	s_and_b32 s32, s2, 1
	s_lshl_b32 s32, s32, 8
	s_add_i32 s4, s4, s32
	s_lshl_b32 s4, s4, s33
	s_add_i32 s4, s4, s5
	s_lshl_b32 s4, s4, 1
	s_lshl_b32 s5, s84, 4
	s_lshl_b32 s5, s5, s33
	s_lshl_b32 s5, s5, 1
	s_add_i32 s4, s4, s5
	s_add_i32 s5, s33, 1
	v_lshlrev_b32_e32 v184, s5, v184
	v_lshl_add_u32 v184, v204, 4, v184
	v_add_u32_e32 v204, s4, v184
	v_mov_b32_e32 v205, 0
	v_lshl_add_u64 v[188:189], v[204:205], 0, s[36:37]
	s_lshl_b32 s88, s93, 2
	s_mov_b32 s89, 0
	s_lshl_b32 s98, s93, 8
	s_mov_b32 s99, 0
	s_waitcnt vmcnt(0)
	s_barrier
	ds_read_b32 v192, v180
	ds_read_b32 v193, v180 offset:64
	ds_read_b32 v194, v180 offset:128
	ds_read_b32 v195, v180 offset:192
	ds_read_b32 v196, v180 offset:512
	ds_read_b32 v197, v180 offset:576
	ds_read_b32 v198, v180 offset:640
	ds_read_b32 v199, v180 offset:704
	s_waitcnt lgkmcnt(0)
	v_mul_f32_e32 v200, v124, v192
	v_mul_f32_e32 v201, v125, v192
	v_cvt_pk_bf16_f32 v200, v200, v201
	ds_write_b16 v173, v200
	ds_write_b16_d16_hi v173, v200 offset:528
	v_mul_f32_e32 v202, v126, v192
	v_mul_f32_e32 v203, v127, v192
	v_cvt_pk_bf16_f32 v202, v202, v203
	ds_write_b16 v173, v202 offset:1056
	ds_write_b16_d16_hi v173, v202 offset:1584
	v_mul_f32_e32 v200, v120, v192
	v_mul_f32_e32 v201, v121, v192
	v_cvt_pk_bf16_f32 v200, v200, v201
	ds_write_b16 v173, v200 offset:2112
	ds_write_b16_d16_hi v173, v200 offset:2640
	v_mul_f32_e32 v202, v122, v192
	v_mul_f32_e32 v203, v123, v192
	v_cvt_pk_bf16_f32 v202, v202, v203
	ds_write_b16 v173, v202 offset:3168
	ds_write_b16_d16_hi v173, v202 offset:3696
	v_mul_f32_e32 v200, v108, v193
	v_mul_f32_e32 v201, v109, v193
	v_cvt_pk_bf16_f32 v200, v200, v201
	ds_write_b16 v173, v200 offset:32
	ds_write_b16_d16_hi v173, v200 offset:560
	v_mul_f32_e32 v202, v110, v193
	v_mul_f32_e32 v203, v111, v193
	v_cvt_pk_bf16_f32 v202, v202, v203
	ds_write_b16 v173, v202 offset:1088
	ds_write_b16_d16_hi v173, v202 offset:1616
	v_mul_f32_e32 v200, v104, v193
	v_mul_f32_e32 v201, v105, v193
	v_cvt_pk_bf16_f32 v200, v200, v201
	ds_write_b16 v173, v200 offset:2144
	ds_write_b16_d16_hi v173, v200 offset:2672
	v_mul_f32_e32 v202, v106, v193
	v_mul_f32_e32 v203, v107, v193
	v_cvt_pk_bf16_f32 v202, v202, v203
	ds_write_b16 v173, v202 offset:3200
	ds_write_b16_d16_hi v173, v202 offset:3728
	v_mul_f32_e32 v200, v92, v194
	v_mul_f32_e32 v201, v93, v194
	v_cvt_pk_bf16_f32 v200, v200, v201
	ds_write_b16 v173, v200 offset:64
	ds_write_b16_d16_hi v173, v200 offset:592
	v_mul_f32_e32 v202, v94, v194
	v_mul_f32_e32 v203, v95, v194
	v_cvt_pk_bf16_f32 v202, v202, v203
	ds_write_b16 v173, v202 offset:1120
	ds_write_b16_d16_hi v173, v202 offset:1648
	v_mul_f32_e32 v200, v88, v194
	v_mul_f32_e32 v201, v89, v194
	v_cvt_pk_bf16_f32 v200, v200, v201
	ds_write_b16 v173, v200 offset:2176
	ds_write_b16_d16_hi v173, v200 offset:2704
	v_mul_f32_e32 v202, v90, v194
	v_mul_f32_e32 v203, v91, v194
	v_cvt_pk_bf16_f32 v202, v202, v203
	ds_write_b16 v173, v202 offset:3232
	ds_write_b16_d16_hi v173, v202 offset:3760
	v_mul_f32_e32 v200, v76, v195
	v_mul_f32_e32 v201, v77, v195
	v_cvt_pk_bf16_f32 v200, v200, v201
	ds_write_b16 v173, v200 offset:96
	ds_write_b16_d16_hi v173, v200 offset:624
	v_mul_f32_e32 v202, v78, v195
	v_mul_f32_e32 v203, v79, v195
	v_cvt_pk_bf16_f32 v202, v202, v203
	ds_write_b16 v173, v202 offset:1152
	ds_write_b16_d16_hi v173, v202 offset:1680
	v_mul_f32_e32 v200, v72, v195
	v_mul_f32_e32 v201, v73, v195
	v_cvt_pk_bf16_f32 v200, v200, v201
	ds_write_b16 v173, v200 offset:2208
	ds_write_b16_d16_hi v173, v200 offset:2736
	v_mul_f32_e32 v202, v74, v195
	v_mul_f32_e32 v203, v75, v195
	v_cvt_pk_bf16_f32 v202, v202, v203
	ds_write_b16 v173, v202 offset:3264
	ds_write_b16_d16_hi v173, v202 offset:3792
	v_mul_f32_e32 v200, v60, v196
	v_mul_f32_e32 v201, v61, v196
	v_cvt_pk_bf16_f32 v200, v200, v201
	ds_write_b16 v173, v200 offset:256
	ds_write_b16_d16_hi v173, v200 offset:784
	v_mul_f32_e32 v202, v62, v196
	v_mul_f32_e32 v203, v63, v196
	v_cvt_pk_bf16_f32 v202, v202, v203
	ds_write_b16 v173, v202 offset:1312
	ds_write_b16_d16_hi v173, v202 offset:1840
	v_mul_f32_e32 v200, v56, v196
	v_mul_f32_e32 v201, v57, v196
	v_cvt_pk_bf16_f32 v200, v200, v201
	ds_write_b16 v173, v200 offset:2368
	ds_write_b16_d16_hi v173, v200 offset:2896
	v_mul_f32_e32 v202, v58, v196
	v_mul_f32_e32 v203, v59, v196
	v_cvt_pk_bf16_f32 v202, v202, v203
	ds_write_b16 v173, v202 offset:3424
	ds_write_b16_d16_hi v173, v202 offset:3952
	v_mul_f32_e32 v200, v44, v197
	v_mul_f32_e32 v201, v45, v197
	v_cvt_pk_bf16_f32 v200, v200, v201
	ds_write_b16 v173, v200 offset:288
	ds_write_b16_d16_hi v173, v200 offset:816
	v_mul_f32_e32 v202, v46, v197
	v_mul_f32_e32 v203, v47, v197
; DI unsigned short f2bf(float f) { return (unsigned short)(cvtpk(f, 0.f) & 0xffffu); }
;     __device__ __forceinline__ static u32x4 pack8(const f32x4& a, const f32x4& b) { u32x4 w; w.x = cvtpk(a[0], a[1]); w.y = cvtpk(a[2], a[3]); w.z = cvtpk(b[0], b[1]); w.w = cvtpk(b[2], b[3]); return w; }
;     __device__ __forceinline__ float rstd_row(const sq_t* sq, int row, float invn) const { return rs_on ? rs_lds[row - rs_base] : rstd_of(sq, row, invn); }
;     __device__ __forceinline__ void operator()(const f32x4 (&acc)[2][2][4][2], const Unit& u, int wr, int wc, int fr, int fq) const {
;     ...
;         } else if (mode == EM_K || mode == EM_V) {
;             bf16_t* kbase = (bf16_t*)(ws + WS_K); bf16_t* vbase = (bf16_t*)(ws + WS_VT);
; #pragma unroll
;             for (int ai = 0; ai < 2; ++ai)
; #pragma unroll
;                 for (int m = 0; m < 4; ++m) { const int row = row0 + ai * HALF + m * 16, pos = row & (S - 1), seq = row >> sshift; const float r = rstd_row(SQKV, row, 1.f / 256.f);
; #pragma unroll
;                     for (int bj = 0; bj < 2; ++bj) { const int C0 = (pn & 1) * 256 + bj * HALF + cw, head = C0 >> 6, w = C0 & 63;
;                         const f32x4 v0 = acc[ai][bj][m][0] * r, v1 = acc[ai][bj][m][1] * r;
;                         if (pn < 2) *(u32x4*)(kbase + (size_t)row * 768 + head * 96 + w) = pack8(v0, v1);
;                         else { bf16_t* vp = vbase + ((size_t)((seq * 8 + head) * 64 + w)) * S + pos;
;                             vp[0] = f2bf(v0[0]); vp[(size_t)S] = f2bf(v0[1]); vp[(size_t)2 * S] = f2bf(v0[2]); vp[(size_t)3 * S] = f2bf(v0[3]);
;                             vp[(size_t)4 * S] = f2bf(v1[0]); vp[(size_t)5 * S] = f2bf(v1[1]); vp[(size_t)6 * S] = f2bf(v1[2]); vp[(size_t)7 * S] = f2bf(v1[3]); } } }
	v_cvt_pk_bf16_f32 v202, v202, v203
	ds_write_b16 v173, v202 offset:1344
	ds_write_b16_d16_hi v173, v202 offset:1872
	v_mul_f32_e32 v200, v40, v197
	v_mul_f32_e32 v201, v41, v197
	v_cvt_pk_bf16_f32 v200, v200, v201
	ds_write_b16 v173, v200 offset:2400
	ds_write_b16_d16_hi v173, v200 offset:2928
	v_mul_f32_e32 v202, v42, v197
	v_mul_f32_e32 v203, v43, v197
	v_cvt_pk_bf16_f32 v202, v202, v203
	ds_write_b16 v173, v202 offset:3456
	ds_write_b16_d16_hi v173, v202 offset:3984
	v_mul_f32_e32 v200, v28, v198
	v_mul_f32_e32 v201, v29, v198
	v_cvt_pk_bf16_f32 v200, v200, v201
	ds_write_b16 v173, v200 offset:320
	ds_write_b16_d16_hi v173, v200 offset:848
	v_mul_f32_e32 v202, v30, v198
	v_mul_f32_e32 v203, v31, v198
	v_cvt_pk_bf16_f32 v202, v202, v203
	ds_write_b16 v173, v202 offset:1376
	ds_write_b16_d16_hi v173, v202 offset:1904
	v_mul_f32_e32 v200, v24, v198
	v_mul_f32_e32 v201, v25, v198
	v_cvt_pk_bf16_f32 v200, v200, v201
	ds_write_b16 v173, v200 offset:2432
	ds_write_b16_d16_hi v173, v200 offset:2960
	v_mul_f32_e32 v202, v26, v198
	v_mul_f32_e32 v203, v27, v198
	v_cvt_pk_bf16_f32 v202, v202, v203
	ds_write_b16 v173, v202 offset:3488
	ds_write_b16_d16_hi v173, v202 offset:4016
	v_mul_f32_e32 v200, v12, v199
	v_mul_f32_e32 v201, v13, v199
	v_cvt_pk_bf16_f32 v200, v200, v201
	ds_write_b16 v173, v200 offset:352
	ds_write_b16_d16_hi v173, v200 offset:880
	v_mul_f32_e32 v202, v14, v199
	v_mul_f32_e32 v203, v15, v199
	v_cvt_pk_bf16_f32 v202, v202, v203
	ds_write_b16 v173, v202 offset:1408
	ds_write_b16_d16_hi v173, v202 offset:1936
	v_mul_f32_e32 v200, v8, v199
	v_mul_f32_e32 v201, v9, v199
	v_cvt_pk_bf16_f32 v200, v200, v201
	ds_write_b16 v173, v200 offset:2464
	ds_write_b16_d16_hi v173, v200 offset:2992
	v_mul_f32_e32 v202, v10, v199
	v_mul_f32_e32 v203, v11, v199
	v_cvt_pk_bf16_f32 v202, v202, v203
	ds_write_b16 v173, v202 offset:3520
	ds_write_b16_d16_hi v173, v202 offset:4048
	s_waitcnt lgkmcnt(0)
	s_barrier
	ds_read_b128 v[216:219], v176
	ds_read_b128 v[220:223], v176 offset:1056
	ds_read_b128 v[224:227], v176 offset:2112
	ds_read_b128 v[228:231], v176 offset:3168
	ds_read_b128 v[234:237], v176 offset:4224
	ds_read_b128 v[238:241], v176 offset:5280
	ds_read_b128 v[242:245], v176 offset:6336
	ds_read_b128 v[246:249], v176 offset:7392
	v_mov_b32_e32 v208, v188
	v_mov_b32_e32 v209, v189
	s_waitcnt lgkmcnt(7)
	global_store_dwordx4 v[208:209], v[216:219], off
	v_lshl_add_u64 v[208:209], v[208:209], 0, s[88:89]
	s_waitcnt lgkmcnt(6)
	global_store_dwordx4 v[208:209], v[220:223], off
	v_lshl_add_u64 v[208:209], v[208:209], 0, s[88:89]
	s_waitcnt lgkmcnt(5)
	global_store_dwordx4 v[208:209], v[224:227], off
	v_lshl_add_u64 v[208:209], v[208:209], 0, s[88:89]
	s_waitcnt lgkmcnt(4)
	global_store_dwordx4 v[208:209], v[228:231], off
	v_lshl_add_u64 v[208:209], v[208:209], 0, s[88:89]
	s_waitcnt lgkmcnt(3)
	global_store_dwordx4 v[208:209], v[234:237], off
	v_lshl_add_u64 v[208:209], v[208:209], 0, s[88:89]
	s_waitcnt lgkmcnt(2)
	global_store_dwordx4 v[208:209], v[238:241], off
	v_lshl_add_u64 v[208:209], v[208:209], 0, s[88:89]
	s_waitcnt lgkmcnt(1)
	global_store_dwordx4 v[208:209], v[242:245], off
	v_lshl_add_u64 v[208:209], v[208:209], 0, s[88:89]
	s_waitcnt lgkmcnt(0)
	global_store_dwordx4 v[208:209], v[246:249], off
	s_barrier
	v_mul_f32_e32 v200, v116, v192
	v_mul_f32_e32 v201, v117, v192
	v_cvt_pk_bf16_f32 v200, v200, v201
	ds_write_b16 v173, v200
	ds_write_b16_d16_hi v173, v200 offset:528
	v_mul_f32_e32 v202, v118, v192
	v_mul_f32_e32 v203, v119, v192
	v_cvt_pk_bf16_f32 v202, v202, v203
	ds_write_b16 v173, v202 offset:1056
	ds_write_b16_d16_hi v173, v202 offset:1584
	v_mul_f32_e32 v200, v112, v192
	v_mul_f32_e32 v201, v113, v192
	v_cvt_pk_bf16_f32 v200, v200, v201
	ds_write_b16 v173, v200 offset:2112
	ds_write_b16_d16_hi v173, v200 offset:2640
	v_mul_f32_e32 v202, v114, v192
	v_mul_f32_e32 v203, v115, v192
	v_cvt_pk_bf16_f32 v202, v202, v203
	ds_write_b16 v173, v202 offset:3168
	ds_write_b16_d16_hi v173, v202 offset:3696
	v_mul_f32_e32 v200, v100, v193
	v_mul_f32_e32 v201, v101, v193
	v_cvt_pk_bf16_f32 v200, v200, v201
	ds_write_b16 v173, v200 offset:32
	ds_write_b16_d16_hi v173, v200 offset:560
	v_mul_f32_e32 v202, v102, v193
	v_mul_f32_e32 v203, v103, v193
	v_cvt_pk_bf16_f32 v202, v202, v203
	ds_write_b16 v173, v202 offset:1088
	ds_write_b16_d16_hi v173, v202 offset:1616
	v_mul_f32_e32 v200, v96, v193
	v_mul_f32_e32 v201, v97, v193
	v_cvt_pk_bf16_f32 v200, v200, v201
	ds_write_b16 v173, v200 offset:2144
	ds_write_b16_d16_hi v173, v200 offset:2672
	v_mul_f32_e32 v202, v98, v193
	v_mul_f32_e32 v203, v99, v193
	v_cvt_pk_bf16_f32 v202, v202, v203
	ds_write_b16 v173, v202 offset:3200
	ds_write_b16_d16_hi v173, v202 offset:3728
	v_mul_f32_e32 v200, v84, v194
	v_mul_f32_e32 v201, v85, v194
	v_cvt_pk_bf16_f32 v200, v200, v201
	ds_write_b16 v173, v200 offset:64
	ds_write_b16_d16_hi v173, v200 offset:592
	v_mul_f32_e32 v202, v86, v194
	v_mul_f32_e32 v203, v87, v194
	v_cvt_pk_bf16_f32 v202, v202, v203
	ds_write_b16 v173, v202 offset:1120
	ds_write_b16_d16_hi v173, v202 offset:1648
	v_mul_f32_e32 v200, v80, v194
	v_mul_f32_e32 v201, v81, v194
	v_cvt_pk_bf16_f32 v200, v200, v201
	ds_write_b16 v173, v200 offset:2176
; DI unsigned short f2bf(float f) { return (unsigned short)(cvtpk(f, 0.f) & 0xffffu); }
;     __device__ __forceinline__ static u32x4 pack8(const f32x4& a, const f32x4& b) { u32x4 w; w.x = cvtpk(a[0], a[1]); w.y = cvtpk(a[2], a[3]); w.z = cvtpk(b[0], b[1]); w.w = cvtpk(b[2], b[3]); return w; }
;     __device__ __forceinline__ float rstd_row(const sq_t* sq, int row, float invn) const { return rs_on ? rs_lds[row - rs_base] : rstd_of(sq, row, invn); }
;     __device__ __forceinline__ void operator()(const f32x4 (&acc)[2][2][4][2], const Unit& u, int wr, int wc, int fr, int fq) const {
;     ...
;         } else if (mode == EM_K || mode == EM_V) {
;             bf16_t* kbase = (bf16_t*)(ws + WS_K); bf16_t* vbase = (bf16_t*)(ws + WS_VT);
; #pragma unroll
;             for (int ai = 0; ai < 2; ++ai)
; #pragma unroll
;                 for (int m = 0; m < 4; ++m) { const int row = row0 + ai * HALF + m * 16, pos = row & (S - 1), seq = row >> sshift; const float r = rstd_row(SQKV, row, 1.f / 256.f);
; #pragma unroll
;                     for (int bj = 0; bj < 2; ++bj) { const int C0 = (pn & 1) * 256 + bj * HALF + cw, head = C0 >> 6, w = C0 & 63;
;                         const f32x4 v0 = acc[ai][bj][m][0] * r, v1 = acc[ai][bj][m][1] * r;
;                         if (pn < 2) *(u32x4*)(kbase + (size_t)row * 768 + head * 96 + w) = pack8(v0, v1);
;                         else { bf16_t* vp = vbase + ((size_t)((seq * 8 + head) * 64 + w)) * S + pos;
;                             vp[0] = f2bf(v0[0]); vp[(size_t)S] = f2bf(v0[1]); vp[(size_t)2 * S] = f2bf(v0[2]); vp[(size_t)3 * S] = f2bf(v0[3]);
;                             vp[(size_t)4 * S] = f2bf(v1[0]); vp[(size_t)5 * S] = f2bf(v1[1]); vp[(size_t)6 * S] = f2bf(v1[2]); vp[(size_t)7 * S] = f2bf(v1[3]); } } }
	ds_write_b16_d16_hi v173, v200 offset:2704
	v_mul_f32_e32 v202, v82, v194
	v_mul_f32_e32 v203, v83, v194
	v_cvt_pk_bf16_f32 v202, v202, v203
	ds_write_b16 v173, v202 offset:3232
	ds_write_b16_d16_hi v173, v202 offset:3760
	v_mul_f32_e32 v200, v68, v195
	v_mul_f32_e32 v201, v69, v195
	v_cvt_pk_bf16_f32 v200, v200, v201
	ds_write_b16 v173, v200 offset:96
	ds_write_b16_d16_hi v173, v200 offset:624
	v_mul_f32_e32 v202, v70, v195
	v_mul_f32_e32 v203, v71, v195
	v_cvt_pk_bf16_f32 v202, v202, v203
	ds_write_b16 v173, v202 offset:1152
	ds_write_b16_d16_hi v173, v202 offset:1680
	v_mul_f32_e32 v200, v64, v195
	v_mul_f32_e32 v201, v65, v195
	v_cvt_pk_bf16_f32 v200, v200, v201
	ds_write_b16 v173, v200 offset:2208
	ds_write_b16_d16_hi v173, v200 offset:2736
	v_mul_f32_e32 v202, v66, v195
	v_mul_f32_e32 v203, v67, v195
	v_cvt_pk_bf16_f32 v202, v202, v203
	ds_write_b16 v173, v202 offset:3264
	ds_write_b16_d16_hi v173, v202 offset:3792
	v_mul_f32_e32 v200, v52, v196
	v_mul_f32_e32 v201, v53, v196
	v_cvt_pk_bf16_f32 v200, v200, v201
	ds_write_b16 v173, v200 offset:256
	ds_write_b16_d16_hi v173, v200 offset:784
	v_mul_f32_e32 v202, v54, v196
	v_mul_f32_e32 v203, v55, v196
	v_cvt_pk_bf16_f32 v202, v202, v203
	ds_write_b16 v173, v202 offset:1312
	ds_write_b16_d16_hi v173, v202 offset:1840
	v_mul_f32_e32 v200, v48, v196
	v_mul_f32_e32 v201, v49, v196
	v_cvt_pk_bf16_f32 v200, v200, v201
	ds_write_b16 v173, v200 offset:2368
	ds_write_b16_d16_hi v173, v200 offset:2896
	v_mul_f32_e32 v202, v50, v196
	v_mul_f32_e32 v203, v51, v196
	v_cvt_pk_bf16_f32 v202, v202, v203
	ds_write_b16 v173, v202 offset:3424
	ds_write_b16_d16_hi v173, v202 offset:3952
	v_mul_f32_e32 v200, v36, v197
	v_mul_f32_e32 v201, v37, v197
	v_cvt_pk_bf16_f32 v200, v200, v201
	ds_write_b16 v173, v200 offset:288
	ds_write_b16_d16_hi v173, v200 offset:816
	v_mul_f32_e32 v202, v38, v197
	v_mul_f32_e32 v203, v39, v197
	v_cvt_pk_bf16_f32 v202, v202, v203
	ds_write_b16 v173, v202 offset:1344
	ds_write_b16_d16_hi v173, v202 offset:1872
	v_mul_f32_e32 v200, v32, v197
	v_mul_f32_e32 v201, v33, v197
	v_cvt_pk_bf16_f32 v200, v200, v201
	ds_write_b16 v173, v200 offset:2400
	ds_write_b16_d16_hi v173, v200 offset:2928
	v_mul_f32_e32 v202, v34, v197
	v_mul_f32_e32 v203, v35, v197
	v_cvt_pk_bf16_f32 v202, v202, v203
	ds_write_b16 v173, v202 offset:3456
	ds_write_b16_d16_hi v173, v202 offset:3984
	v_mul_f32_e32 v200, v20, v198
	v_mul_f32_e32 v201, v21, v198
	v_cvt_pk_bf16_f32 v200, v200, v201
	ds_write_b16 v173, v200 offset:320
	ds_write_b16_d16_hi v173, v200 offset:848
	v_mul_f32_e32 v202, v22, v198
	v_mul_f32_e32 v203, v23, v198
	v_cvt_pk_bf16_f32 v202, v202, v203
	ds_write_b16 v173, v202 offset:1376
	ds_write_b16_d16_hi v173, v202 offset:1904
	v_mul_f32_e32 v200, v16, v198
	v_mul_f32_e32 v201, v17, v198
	v_cvt_pk_bf16_f32 v200, v200, v201
	ds_write_b16 v173, v200 offset:2432
	ds_write_b16_d16_hi v173, v200 offset:2960
	v_mul_f32_e32 v202, v18, v198
	v_mul_f32_e32 v203, v19, v198
	v_cvt_pk_bf16_f32 v202, v202, v203
	ds_write_b16 v173, v202 offset:3488
	ds_write_b16_d16_hi v173, v202 offset:4016
	v_mul_f32_e32 v200, v4, v199
	v_mul_f32_e32 v201, v5, v199
	v_cvt_pk_bf16_f32 v200, v200, v201
	ds_write_b16 v173, v200 offset:352
	ds_write_b16_d16_hi v173, v200 offset:880
	v_mul_f32_e32 v202, v6, v199
	v_mul_f32_e32 v203, v7, v199
	v_cvt_pk_bf16_f32 v202, v202, v203
	ds_write_b16 v173, v202 offset:1408
	ds_write_b16_d16_hi v173, v202 offset:1936
	v_mul_f32_e32 v200, v0, v199
	v_mul_f32_e32 v201, v1, v199
	v_cvt_pk_bf16_f32 v200, v200, v201
	ds_write_b16 v173, v200 offset:2464
	ds_write_b16_d16_hi v173, v200 offset:2992
	v_mul_f32_e32 v202, v2, v199
	v_mul_f32_e32 v203, v3, v199
	v_cvt_pk_bf16_f32 v202, v202, v203
	ds_write_b16 v173, v202 offset:3520
	ds_write_b16_d16_hi v173, v202 offset:4048
	s_waitcnt lgkmcnt(0)
	s_barrier
	ds_read_b128 v[216:219], v176
	ds_read_b128 v[220:223], v176 offset:1056
	ds_read_b128 v[224:227], v176 offset:2112
	ds_read_b128 v[228:231], v176 offset:3168
	ds_read_b128 v[234:237], v176 offset:4224
	ds_read_b128 v[238:241], v176 offset:5280
	ds_read_b128 v[242:245], v176 offset:6336
	ds_read_b128 v[246:249], v176 offset:7392
	v_lshl_add_u64 v[208:209], v[188:189], 0, s[98:99]
	s_waitcnt lgkmcnt(7)
	global_store_dwordx4 v[208:209], v[216:219], off
	v_lshl_add_u64 v[208:209], v[208:209], 0, s[88:89]
	s_waitcnt lgkmcnt(6)
	global_store_dwordx4 v[208:209], v[220:223], off
	v_lshl_add_u64 v[208:209], v[208:209], 0, s[88:89]
	s_waitcnt lgkmcnt(5)
	global_store_dwordx4 v[208:209], v[224:227], off
	v_lshl_add_u64 v[208:209], v[208:209], 0, s[88:89]
	s_waitcnt lgkmcnt(4)
	global_store_dwordx4 v[208:209], v[228:231], off
	v_lshl_add_u64 v[208:209], v[208:209], 0, s[88:89]
	s_waitcnt lgkmcnt(3)
	global_store_dwordx4 v[208:209], v[234:237], off
	v_lshl_add_u64 v[208:209], v[208:209], 0, s[88:89]
	s_waitcnt lgkmcnt(2)
	global_store_dwordx4 v[208:209], v[238:241], off
	v_lshl_add_u64 v[208:209], v[208:209], 0, s[88:89]
	s_waitcnt lgkmcnt(1)
	global_store_dwordx4 v[208:209], v[242:245], off
	v_lshl_add_u64 v[208:209], v[208:209], 0, s[88:89]
	s_waitcnt lgkmcnt(0)
	global_store_dwordx4 v[208:209], v[246:249], off
	s_branch .LBB0_915
